# v13 + FFN-up EpiConvGate conv-weight loads hoisted from the epilogue to the tile header (before the K-loop)
# baseline (speedup 1.0000x reference)
.LBB0_1157:
	s_lshl_b32 s2, s60, 7
	v_add_u32_e32 v240, s2, v192
	v_ashrrev_i32_e32 v241, 31, v240
	v_lshlrev_b64 v[240:241], 2, v[240:241]
	v_lshl_add_u64 v[244:245], s[86:87], 0, v[240:241]
	v_lshl_add_u64 v[242:243], s[38:39], 0, v[240:241]
	v_lshl_add_u64 v[240:241], v[244:245], 0, s[12:13]
	v_lshl_add_u64 v[244:245], v[244:245], 0, s[14:15]
	v_cndmask_b32_e64 v241, v243, v241, s[0:1]
	v_cndmask_b32_e64 v240, v242, v240, s[0:1]
	v_cndmask_b32_e64 v243, v243, v245, s[42:43]
	v_cndmask_b32_e64 v242, v242, v244, s[42:43]
	global_load_dword v238, v[240:241], off
	global_load_dword v239, v[242:243], off
	s_ashr_i32 s91, s90, 31
	s_lshl_b64 s[2:3], s[90:91], 20
	v_readlane_b32 s74, v253, 17
	v_readlane_b32 s75, v253, 18
	s_add_u32 s82, s74, s2
	s_addc_u32 s83, s75, s3
	s_and_b64 s[2:3], s[58:59], exec
	s_cselect_b32 s23, s83, s63
	s_cselect_b32 s61, s82, s62
	s_ashr_i32 s93, s92, 31
	s_lshl_b64 s[2:3], s[92:93], 20
	s_add_u32 s74, s77, s2
	s_addc_u32 s75, s4, s3
	s_and_b64 s[2:3], s[58:59], exec
	s_cselect_b32 s91, s75, s35
	s_cselect_b32 s93, s74, s34
	s_add_u32 s2, s34, 0x100
	v_mov_b32_e32 v56, 0
	s_addc_u32 s3, s35, 0
	s_mov_b32 s6, -2
	v_mov_b32_e32 v57, v56
	v_mov_b32_e32 v58, v56
	v_mov_b32_e32 v59, v56
	v_mov_b32_e32 v52, v56
	v_mov_b32_e32 v53, v56
	v_mov_b32_e32 v54, v56
	v_mov_b32_e32 v55, v56
	v_mov_b32_e32 v44, v56
	v_mov_b32_e32 v45, v56
	v_mov_b32_e32 v46, v56
	v_mov_b32_e32 v47, v56
	v_mov_b32_e32 v40, v56
	v_mov_b32_e32 v41, v56
	v_mov_b32_e32 v42, v56
	v_mov_b32_e32 v43, v56
	v_mov_b32_e32 v36, v56
	v_mov_b32_e32 v37, v56
	v_mov_b32_e32 v38, v56
	v_mov_b32_e32 v39, v56
	v_mov_b32_e32 v32, v56
	v_mov_b32_e32 v33, v56
	v_mov_b32_e32 v34, v56
	v_mov_b32_e32 v35, v56
	v_mov_b32_e32 v24, v56
	v_mov_b32_e32 v25, v56
	v_mov_b32_e32 v26, v56
	v_mov_b32_e32 v27, v56
	v_mov_b32_e32 v16, v56
	v_mov_b32_e32 v17, v56
	v_mov_b32_e32 v18, v56
	v_mov_b32_e32 v19, v56
	v_mov_b32_e32 v20, v56
	v_mov_b32_e32 v21, v56
	v_mov_b32_e32 v22, v56
	v_mov_b32_e32 v23, v56
	v_mov_b32_e32 v12, v56
	v_mov_b32_e32 v13, v56
	v_mov_b32_e32 v14, v56
	v_mov_b32_e32 v15, v56
	v_mov_b32_e32 v0, v56
	v_mov_b32_e32 v1, v56
	v_mov_b32_e32 v2, v56
	v_mov_b32_e32 v3, v56
	v_mov_b32_e32 v4, v56
	v_mov_b32_e32 v5, v56
	v_mov_b32_e32 v6, v56
	v_mov_b32_e32 v7, v56
	v_mov_b32_e32 v64, v56
	v_mov_b32_e32 v65, v56
	v_mov_b32_e32 v66, v56
	v_mov_b32_e32 v67, v56
	v_mov_b32_e32 v68, v56
	v_mov_b32_e32 v69, v56
	v_mov_b32_e32 v70, v56
	v_mov_b32_e32 v71, v56
	v_mov_b32_e32 v8, v56
	v_mov_b32_e32 v9, v56
	v_mov_b32_e32 v10, v56
	v_mov_b32_e32 v11, v56
	v_mov_b32_e32 v72, v56
	v_mov_b32_e32 v73, v56
	v_mov_b32_e32 v74, v56
	v_mov_b32_e32 v75, v56
	v_mov_b32_e32 v76, v56
	v_mov_b32_e32 v77, v56
	v_mov_b32_e32 v78, v56
	v_mov_b32_e32 v79, v56
	v_mov_b32_e32 v80, v56
	v_mov_b32_e32 v81, v56
	v_mov_b32_e32 v82, v56
	v_mov_b32_e32 v83, v56
	v_mov_b32_e32 v84, v56
	v_mov_b32_e32 v85, v56
	v_mov_b32_e32 v86, v56
	v_mov_b32_e32 v87, v56
	v_mov_b32_e32 v28, v56
	v_mov_b32_e32 v29, v56
	v_mov_b32_e32 v30, v56
	v_mov_b32_e32 v31, v56
	v_mov_b32_e32 v88, v56
	v_mov_b32_e32 v89, v56
	v_mov_b32_e32 v90, v56
	v_mov_b32_e32 v91, v56
	v_mov_b32_e32 v92, v56
	v_mov_b32_e32 v93, v56
	v_mov_b32_e32 v94, v56
	v_mov_b32_e32 v95, v56
	v_mov_b32_e32 v98, v56
	v_mov_b32_e32 v99, v56
	v_mov_b32_e32 v100, v56
	v_mov_b32_e32 v101, v56
	v_mov_b32_e32 v48, v56
	v_mov_b32_e32 v49, v56
	v_mov_b32_e32 v50, v56
	v_mov_b32_e32 v51, v56
	v_mov_b32_e32 v102, v56
	v_mov_b32_e32 v103, v56
	v_mov_b32_e32 v104, v56
	v_mov_b32_e32 v105, v56
	v_mov_b32_e32 v106, v56
	v_mov_b32_e32 v107, v56
	v_mov_b32_e32 v108, v56
	v_mov_b32_e32 v109, v56
	v_mov_b32_e32 v110, v56
	v_mov_b32_e32 v111, v56
	v_mov_b32_e32 v112, v56
	v_mov_b32_e32 v113, v56
	v_mov_b32_e32 v114, v56
	v_mov_b32_e32 v115, v56
	v_mov_b32_e32 v116, v56
	v_mov_b32_e32 v117, v56
	v_mov_b32_e32 v60, v56
	v_mov_b32_e32 v61, v56
	v_mov_b32_e32 v62, v56
	v_mov_b32_e32 v63, v56
	v_mov_b32_e32 v118, v56
	v_mov_b32_e32 v119, v56
	v_mov_b32_e32 v120, v56
	v_mov_b32_e32 v121, v56
	v_mov_b32_e32 v122, v56
	v_mov_b32_e32 v123, v56
	v_mov_b32_e32 v124, v56
	v_mov_b32_e32 v125, v56
	v_mov_b32_e32 v126, v56
	v_mov_b32_e32 v127, v56
	v_mov_b32_e32 v128, v56
	v_mov_b32_e32 v129, v56

.LBB0_1161:
	s_lshl_b32 s2, s60, 7
	v_cmp_gt_i32_e32 vcc, 15, v190
	s_nop 0
	s_nop 0
	s_nop 0
	s_nop 0
	s_nop 0
	s_nop 0
	s_nop 0
	s_nop 0
	s_nop 0
	s_nop 0
	s_nop 0
	s_nop 0
	s_nop 0
	s_nop 0
	s_nop 0
	s_mov_b64 s[60:61], -1
	s_and_saveexec_b64 s[34:35], vcc
	v_cmp_eq_u32_e32 vcc, 0, v190
	s_orn2_b64 s[60:61], vcc, exec
	s_or_b64 exec, exec, s[34:35]
	s_and_saveexec_b64 s[34:35], s[60:61]
	v_readlane_b32 s88, v253, 7
	v_readlane_b32 s89, v253, 8
	s_cbranch_execz .LBB0_1165
	v_cndmask_b32_e64 v135, v117, v129, s[48:49]
	v_cndmask_b32_e64 v134, v116, v128, s[48:49]
	v_cndmask_b32_e64 v133, v115, v127, s[48:49]
	v_cndmask_b32_e64 v132, v114, v126, s[48:49]
	ds_write_b128 v215, v[132:135]
	v_cndmask_b32_e64 v135, v47, v59, s[48:49]
	v_cndmask_b32_e64 v134, v46, v58, s[48:49]
	v_cndmask_b32_e64 v133, v45, v57, s[48:49]
	v_cndmask_b32_e64 v132, v44, v56, s[48:49]
	ds_write_b128 v215, v[132:135] offset:16
	v_cndmask_b32_e64 v135, v101, v113, s[48:49]
	v_cndmask_b32_e64 v134, v100, v112, s[48:49]
	v_cndmask_b32_e64 v133, v99, v111, s[48:49]
	v_cndmask_b32_e64 v132, v98, v110, s[48:49]
	ds_write_b128 v215, v[132:135] offset:32
	v_cndmask_b32_e64 v135, v35, v43, s[48:49]
	v_cndmask_b32_e64 v134, v34, v42, s[48:49]
	v_cndmask_b32_e64 v133, v33, v41, s[48:49]
	v_cndmask_b32_e64 v132, v32, v40, s[48:49]
	ds_write_b128 v215, v[132:135] offset:48
	v_cndmask_b32_e64 v135, v83, v95, s[48:49]
	v_cndmask_b32_e64 v134, v82, v94, s[48:49]
	v_cndmask_b32_e64 v133, v81, v93, s[48:49]
	v_cndmask_b32_e64 v132, v80, v92, s[48:49]
	ds_write_b128 v216, v[132:135]
	v_cndmask_b32_e64 v135, v23, v27, s[48:49]
	v_cndmask_b32_e64 v134, v22, v26, s[48:49]
	v_cndmask_b32_e64 v133, v21, v25, s[48:49]
	v_cndmask_b32_e64 v132, v20, v24, s[48:49]
	ds_write_b128 v216, v[132:135] offset:16
	v_cndmask_b32_e64 v135, v67, v79, s[48:49]
	v_cndmask_b32_e64 v134, v66, v78, s[48:49]
	v_cndmask_b32_e64 v133, v65, v77, s[48:49]
	v_cndmask_b32_e64 v132, v64, v76, s[48:49]
	ds_write_b128 v216, v[132:135] offset:32
	v_cndmask_b32_e64 v135, v7, v15, s[48:49]
	v_cndmask_b32_e64 v134, v6, v14, s[48:49]
	v_cndmask_b32_e64 v133, v5, v13, s[48:49]
	v_cndmask_b32_e64 v132, v4, v12, s[48:49]
	ds_write_b128 v216, v[132:135] offset:48
.LBB0_1165:
	s_or_b64 exec, exec, s[34:35]
	s_waitcnt vmcnt(0)
	ds_write2st64_b32 v217, v238, v239 offset1:8
	s_waitcnt vmcnt(0) lgkmcnt(0)
	s_barrier
	v_or_b32_e32 v188, s2, v193
	v_ashrrev_i32_e32 v189, 31, v188
	s_and_saveexec_b64 s[2:3], s[96:97]
	s_xor_b64 s[34:35], exec, s[2:3]
	s_andn2_saveexec_b64 s[34:35], s[34:35]
	s_cbranch_execz .LBB0_1167
	s_ashr_i32 s23, s22, 31
	v_readlane_b32 s60, v252, 48
	s_lshl_b64 s[2:3], s[22:23], 2
	v_cndmask_b32_e64 v130, 2, 0, s[46:47]
	v_readlane_b32 s61, v252, 49
	v_or_b32_e32 v132, s2, v130
	s_mov_b32 s2, 0xb000
	v_mov_b64_e32 v[130:131], s[60:61]
	v_mad_u64_u32 v[130:131], s[60:61], v132, s2, v[130:131]
	v_mov_b32_e32 v132, 0xb000
	v_mad_i32_i24 v131, s3, v132, v131
	v_lshl_add_u64 v[134:135], v[188:189], 2, v[130:131]
	v_cndmask_b32_e64 v133, v87, v129, s[46:47]
	v_cndmask_b32_e64 v132, v86, v128, s[46:47]
	v_cndmask_b32_e64 v131, v85, v127, s[46:47]
	v_cndmask_b32_e64 v130, v84, v126, s[46:47]
	v_add_co_u32_e32 v136, vcc, s2, v134
	global_store_dwordx4 v[134:135], v[130:133], off
	s_nop 0
	v_addc_co_u32_e32 v137, vcc, 0, v135, vcc
	v_cndmask_b32_e64 v133, v83, v125, s[46:47]
	v_cndmask_b32_e64 v132, v82, v124, s[46:47]
	v_cndmask_b32_e64 v131, v81, v123, s[46:47]
	v_cndmask_b32_e64 v130, v80, v122, s[46:47]
	global_store_dwordx4 v[136:137], v[130:133], off
	s_movk_i32 s2, 0x5000
	s_nop 0
	v_cndmask_b32_e64 v133, v19, v59, s[46:47]
	v_cndmask_b32_e64 v132, v18, v58, s[46:47]
	v_cndmask_b32_e64 v131, v17, v57, s[46:47]
	v_cndmask_b32_e64 v130, v16, v56, s[46:47]
	global_store_dwordx4 v[134:135], v[130:133], off offset:16
	s_nop 1
	v_cndmask_b32_e64 v133, v23, v55, s[46:47]
	v_cndmask_b32_e64 v132, v22, v54, s[46:47]
	v_cndmask_b32_e64 v131, v21, v53, s[46:47]
	v_cndmask_b32_e64 v130, v20, v52, s[46:47]
	global_store_dwordx4 v[136:137], v[130:133], off offset:16
	v_add_co_u32_e32 v136, vcc, s2, v134
	s_mov_b32 s2, 0x10000
	s_nop 0
	v_addc_co_u32_e32 v137, vcc, 0, v135, vcc
	v_cndmask_b32_e64 v133, v71, v113, s[46:47]
	v_cndmask_b32_e64 v132, v70, v112, s[46:47]
	v_cndmask_b32_e64 v131, v69, v111, s[46:47]
	v_cndmask_b32_e64 v130, v68, v110, s[46:47]
	v_add_co_u32_e32 v134, vcc, s2, v134
	global_store_dwordx4 v[136:137], v[130:133], off offset:2048
	s_nop 0
	v_addc_co_u32_e32 v135, vcc, 0, v135, vcc
	v_cndmask_b32_e64 v133, v67, v109, s[46:47]
	v_cndmask_b32_e64 v132, v66, v108, s[46:47]
	v_cndmask_b32_e64 v131, v65, v107, s[46:47]
	v_cndmask_b32_e64 v130, v64, v106, s[46:47]
	global_store_dwordx4 v[134:135], v[130:133], off offset:2048
	s_nop 1
	v_cndmask_b32_e64 v133, v3, v43, s[46:47]
	v_cndmask_b32_e64 v132, v2, v42, s[46:47]
	v_cndmask_b32_e64 v131, v1, v41, s[46:47]
	v_cndmask_b32_e64 v130, v0, v40, s[46:47]
	global_store_dwordx4 v[136:137], v[130:133], off offset:2064
	s_nop 1
	v_cndmask_b32_e64 v133, v7, v39, s[46:47]
	v_cndmask_b32_e64 v132, v6, v38, s[46:47]
	v_cndmask_b32_e64 v131, v5, v37, s[46:47]
	v_cndmask_b32_e64 v130, v4, v36, s[46:47]
	global_store_dwordx4 v[134:135], v[130:133], off offset:2064
